# in-proj / ffn-up rstd prologues: all tiles' partial-sum loads issued into separate register banks, one wait, reductions at the join (block counts from the launch shape)
# speedup vs baseline: 1.0015x; 1.0015x over previous
; __device__ __forceinline__ float row_rstd(const float* ssq, int row, float inv_n) {
;     const f32x4* p = (const f32x4*)(ssq + (size_t)row * 32);
;     f32x4 s = p[0];
; #pragma unroll
;     for (int i = 1; i < 8; ++i) s += p[i];
;     return rsqrtf((s[0] + s[1] + s[2] + s[3]) * inv_n + NORM_EPS);
; }
;     __device__ bool next(int i, Unit& u) const {
;         const long L = (long)i * G + c; if (L >= nwg) return false;
;         int wgid = (int)L; { const int q = nwg / NXCD, r = nwg % NXCD, xcd = wgid % NXCD, off = wgid / NXCD; wgid = (xcd < r ? xcd * (q + 1) : r * (q + 1) + (xcd - r) * q) + off; }
;         const int nig = WGM * nN, gid = wgid / nig, fm = gid * WGM, gsz = (nM - fm) < WGM ? (nM - fm) : WGM;
;         u.pm = fm + ((wgid % nig) % gsz); u.pn = (wgid % nig) / gsz; return true;
;     }
.LBB0_29:
	v_readlane_b32 s0, v253, 16
	s_add_u32 s8, s62, 0x1ce00000
	s_addc_u32 s9, s63, 0
	v_lshl_add_u32 v150, v245, 2, s0
	s_movk_i32 s0, 0x100
	v_cmp_gt_i32_e64 s[38:39], s0, v245
	s_and_saveexec_b64 s[0:1], s[38:39]
	s_cbranch_execz .LBB0_31
	s_ashr_i32 s4, s4, 3
	s_add_i32 s4, s5, s4
	s_ashr_i32 s5, s4, 31
	s_lshr_b32 s5, s5, 24
	s_add_i32 s5, s4, s5
	s_and_b32 s29, s5, 0xff00
	s_sub_i32 s4, s4, s29
	s_sext_i32_i16 s29, s4
	s_bfe_u32 s29, s29, 0x3001c
	s_add_i32 s29, s4, s29
	s_and_b32 s29, s29, 0xfff8
	s_sub_i32 s4, s4, s29
	s_sext_i32_i16 s4, s4
	s_lshl_b32 s5, s5, 3
	s_and_b32 s5, s5, 0xfffff800
	s_lshl_b32 s4, s4, 8
	s_add_i32 s4, s4, s5
	v_add_u32_e32 v0, s4, v245
	v_ashrrev_i32_e32 v1, 31, v0
	v_lshlrev_b64 v[0:1], 7, v[0:1]
	v_lshl_add_u64 v[0:1], s[8:9], 0, v[0:1]
	s_waitcnt lgkmcnt(0)
	global_load_dwordx4 v[36:39], v[0:1], off
	global_load_dwordx4 v[40:43], v[0:1], off offset:16
	global_load_dwordx4 v[44:47], v[0:1], off offset:32
	global_load_dwordx4 v[48:51], v[0:1], off offset:48
	global_load_dwordx4 v[52:55], v[0:1], off offset:64
	global_load_dwordx4 v[56:59], v[0:1], off offset:80
	global_load_dwordx4 v[60:63], v[0:1], off offset:96
	global_load_dwordx4 v[64:67], v[0:1], off offset:112

; __device__ __forceinline__ float row_rstd(const float* ssq, int row, float inv_n) {
;     const f32x4* p = (const f32x4*)(ssq + (size_t)row * 32);
;     f32x4 s = p[0];
; #pragma unroll
;     for (int i = 1; i < 8; ++i) s += p[i];
;     return rsqrtf((s[0] + s[1] + s[2] + s[3]) * inv_n + NORM_EPS);
; }
;     __device__ bool next(int i, Unit& u) const {
;         const long L = (long)i * G + c; if (L >= nwg) return false;
;         int wgid = (int)L; { const int q = nwg / NXCD, r = nwg % NXCD, xcd = wgid % NXCD, off = wgid / NXCD; wgid = (xcd < r ? xcd * (q + 1) : r * (q + 1) + (xcd - r) * q) + off; }
;         const int nig = WGM * nN, gid = wgid / nig, fm = gid * WGM, gsz = (nM - fm) < WGM ? (nM - fm) : WGM;
;         u.pm = fm + ((wgid % nig) % gsz); u.pn = (wgid % nig) / gsz; return true;
;     }
.LBB0_35:
	s_ashr_i32 s29, s29, 3
	s_add_i32 s29, s31, s29
	s_ashr_i32 s31, s29, 31
	s_lshr_b32 s31, s31, 24
	s_add_i32 s31, s29, s31
	s_ashr_i32 s34, s31, 8
	s_and_b32 s31, s31, 0xffffff00
	s_sub_i32 s29, s29, s31
	s_lshl_b32 s31, s34, 3
	s_sub_i32 s34, 32, s31
	s_min_i32 s34, s34, 8
	s_abs_i32 s34, s34
	v_cvt_f32_u32_e32 v0, s34
	s_sub_i32 s36, 0, s34
	s_ashr_i32 s35, s29, 31
	s_abs_i32 s29, s29
	v_rcp_iflag_f32_e32 v0, v0
	s_nop 0
	v_mul_f32_e32 v0, 0x4f7ffffe, v0
	v_cvt_u32_f32_e32 v0, v0
	s_nop 0
	v_readfirstlane_b32 s37, v0
	s_mul_i32 s36, s36, s37
	s_mul_hi_u32 s36, s37, s36
	s_add_i32 s37, s37, s36
	s_mul_hi_u32 s36, s29, s37
	s_mul_i32 s36, s36, s34
	s_sub_i32 s29, s29, s36
	s_sub_i32 s36, s29, s34
	s_cmp_ge_u32 s29, s34
	s_cselect_b32 s29, s36, s29
	s_sub_i32 s36, s29, s34
	s_cmp_ge_u32 s29, s34
	s_cselect_b32 s29, s36, s29
	s_xor_b32 s29, s29, s35
	s_sub_i32 s29, s29, s35
	s_add_i32 s29, s29, s31
	v_lshl_add_u32 v0, s29, 8, v245
	v_ashrrev_i32_e32 v1, 31, v0
	v_lshlrev_b64 v[0:1], 7, v[0:1]
	v_lshl_add_u64 v[0:1], s[8:9], 0, v[0:1]
	s_waitcnt lgkmcnt(0)
	global_load_dwordx4 v[68:71], v[0:1], off
	global_load_dwordx4 v[72:75], v[0:1], off offset:16
	global_load_dwordx4 v[76:79], v[0:1], off offset:32
	global_load_dwordx4 v[80:83], v[0:1], off offset:48
	global_load_dwordx4 v[84:87], v[0:1], off offset:64
	global_load_dwordx4 v[88:91], v[0:1], off offset:80
	global_load_dwordx4 v[92:95], v[0:1], off offset:96
	global_load_dwordx4 v[96:99], v[0:1], off offset:112

; __device__ __forceinline__ float row_rstd(const float* ssq, int row, float inv_n) {
;     const f32x4* p = (const f32x4*)(ssq + (size_t)row * 32);
;     f32x4 s = p[0];
; #pragma unroll
;     for (int i = 1; i < 8; ++i) s += p[i];
;     return rsqrtf((s[0] + s[1] + s[2] + s[3]) * inv_n + NORM_EPS);
; }
;     __device__ bool next(int i, Unit& u) const {
;         const long L = (long)i * G + c; if (L >= nwg) return false;
;         int wgid = (int)L; { const int q = nwg / NXCD, r = nwg % NXCD, xcd = wgid % NXCD, off = wgid / NXCD; wgid = (xcd < r ? xcd * (q + 1) : r * (q + 1) + (xcd - r) * q) + off; }
;         const int nig = WGM * nN, gid = wgid / nig, fm = gid * WGM, gsz = (nM - fm) < WGM ? (nM - fm) : WGM;
;         u.pm = fm + ((wgid % nig) % gsz); u.pn = (wgid % nig) / gsz; return true;
;     }
.LBB0_40:
	s_ashr_i32 s29, s29, 3
	s_add_i32 s29, s31, s29
	s_ashr_i32 s31, s29, 31
	s_lshr_b32 s31, s31, 24
	s_add_i32 s31, s29, s31
	s_ashr_i32 s34, s31, 8
	s_and_b32 s31, s31, 0xffffff00
	s_sub_i32 s29, s29, s31
	s_lshl_b32 s31, s34, 3
	s_sub_i32 s34, 32, s31
	s_min_i32 s34, s34, 8
	s_abs_i32 s34, s34
	v_cvt_f32_u32_e32 v0, s34
	s_sub_i32 s36, 0, s34
	s_ashr_i32 s35, s29, 31
	s_abs_i32 s29, s29
	v_rcp_iflag_f32_e32 v0, v0
	s_nop 0
	v_mul_f32_e32 v0, 0x4f7ffffe, v0
	v_cvt_u32_f32_e32 v0, v0
	s_nop 0
	v_readfirstlane_b32 s37, v0
	s_mul_i32 s36, s36, s37
	s_mul_hi_u32 s36, s37, s36
	s_add_i32 s37, s37, s36
	s_mul_hi_u32 s36, s29, s37
	s_mul_i32 s36, s36, s34
	s_sub_i32 s29, s29, s36
	s_sub_i32 s36, s29, s34
	s_cmp_ge_u32 s29, s34
	s_cselect_b32 s29, s36, s29
	s_sub_i32 s36, s29, s34
	s_cmp_ge_u32 s29, s34
	s_cselect_b32 s29, s36, s29
	s_xor_b32 s29, s29, s35
	s_sub_i32 s29, s29, s35
	s_add_i32 s29, s29, s31
	v_lshl_add_u32 v0, s29, 8, v245
	v_ashrrev_i32_e32 v1, 31, v0
	v_lshlrev_b64 v[0:1], 7, v[0:1]
	v_lshl_add_u64 v[0:1], s[8:9], 0, v[0:1]
	s_waitcnt lgkmcnt(0)
	global_load_dwordx4 v[100:103], v[0:1], off
	global_load_dwordx4 v[104:107], v[0:1], off offset:16
	global_load_dwordx4 v[108:111], v[0:1], off offset:32
	global_load_dwordx4 v[112:115], v[0:1], off offset:48
	global_load_dwordx4 v[116:119], v[0:1], off offset:64
	global_load_dwordx4 v[120:123], v[0:1], off offset:80
	global_load_dwordx4 v[124:127], v[0:1], off offset:96
	global_load_dwordx4 v[128:131], v[0:1], off offset:112

; __device__ __forceinline__ float row_rstd(const float* ssq, int row, float inv_n) {
;     const f32x4* p = (const f32x4*)(ssq + (size_t)row * 32);
;     f32x4 s = p[0];
; #pragma unroll
;     for (int i = 1; i < 8; ++i) s += p[i];
;     return rsqrtf((s[0] + s[1] + s[2] + s[3]) * inv_n + NORM_EPS);
; }
;     __device__ bool next(int i, Unit& u) const {
;         const long L = (long)i * G + c; if (L >= nwg) return false;
;         int wgid = (int)L; { const int q = nwg / NXCD, r = nwg % NXCD, xcd = wgid % NXCD, off = wgid / NXCD; wgid = (xcd < r ? xcd * (q + 1) : r * (q + 1) + (xcd - r) * q) + off; }
;         const int nig = WGM * nN, gid = wgid / nig, fm = gid * WGM, gsz = (nM - fm) < WGM ? (nM - fm) : WGM;
;         u.pm = fm + ((wgid % nig) % gsz); u.pn = (wgid % nig) / gsz; return true;
;     }
.LBB0_45:
	s_ashr_i32 s29, s29, 3
	s_add_i32 s29, s31, s29
	s_ashr_i32 s31, s29, 31
	s_lshr_b32 s31, s31, 24
	s_add_i32 s31, s29, s31
	s_ashr_i32 s34, s31, 8
	s_and_b32 s31, s31, 0xffffff00
	s_sub_i32 s29, s29, s31
	s_lshl_b32 s31, s34, 3
	s_sub_i32 s34, 32, s31
	s_min_i32 s34, s34, 8
	s_abs_i32 s34, s34
	v_cvt_f32_u32_e32 v0, s34
	s_sub_i32 s36, 0, s34
	s_ashr_i32 s35, s29, 31
	s_abs_i32 s29, s29
	v_rcp_iflag_f32_e32 v0, v0
	s_nop 0
	v_mul_f32_e32 v0, 0x4f7ffffe, v0
	v_cvt_u32_f32_e32 v0, v0
	s_nop 0
	v_readfirstlane_b32 s37, v0
	s_mul_i32 s36, s36, s37
	s_mul_hi_u32 s36, s37, s36
	s_add_i32 s37, s37, s36
	s_mul_hi_u32 s36, s29, s37
	s_mul_i32 s36, s36, s34
	s_sub_i32 s29, s29, s36
	s_sub_i32 s36, s29, s34
	s_cmp_ge_u32 s29, s34
	s_cselect_b32 s29, s36, s29
	s_sub_i32 s36, s29, s34
	s_cmp_ge_u32 s29, s34
	s_cselect_b32 s29, s36, s29
	s_xor_b32 s29, s29, s35
	s_sub_i32 s29, s29, s35
	s_add_i32 s29, s29, s31
	v_lshl_add_u32 v0, s29, 8, v245
	v_ashrrev_i32_e32 v1, 31, v0
	v_lshlrev_b64 v[0:1], 7, v[0:1]
	v_lshl_add_u64 v[0:1], s[8:9], 0, v[0:1]
	s_waitcnt lgkmcnt(0)
	global_load_dwordx4 v[152:155], v[0:1], off
	global_load_dwordx4 v[156:159], v[0:1], off offset:16
	global_load_dwordx4 v[160:163], v[0:1], off offset:32
	global_load_dwordx4 v[164:167], v[0:1], off offset:48
	global_load_dwordx4 v[168:171], v[0:1], off offset:64
	global_load_dwordx4 v[172:175], v[0:1], off offset:80
	global_load_dwordx4 v[176:179], v[0:1], off offset:96
	global_load_dwordx4 v[180:183], v[0:1], off offset:112

; #define LAS __attribute__((address_space(3)))
; __device__ __forceinline__ float row_rstd(const float* ssq, int row, float inv_n) {
;     const f32x4* p = (const f32x4*)(ssq + (size_t)row * 32);
;     f32x4 s = p[0];
; #pragma unroll
;     for (int i = 1; i < 8; ++i) s += p[i];
;     return rsqrtf((s[0] + s[1] + s[2] + s[3]) * inv_n + NORM_EPS);
; }
;     __device__ __forceinline__ void prepare(const pg8::Unit& u, LAS unsigned char* lds, int buf, int tid) const {
;         if (tid < 256) ((LAS float*)(lds + pg8::STAGE_BYTES))[buf * 256 + tid] = row_rstd(ssq, u.pm * 256 + tid, 1.0f / DM);
;     }
.LBB0_67:
	s_movk_i32 s34, 0x100
	v_cmp_gt_i32_e32 vcc, s34, v245
	s_and_saveexec_b64 s[34:35], vcc
	s_cbranch_execz .Lrs_done_b
	s_waitcnt vmcnt(0)
	v_pk_add_f32 v[36:37], v[36:37], v[40:41]
	v_pk_add_f32 v[0:1], v[38:39], v[42:43]
	v_pk_add_f32 v[36:37], v[36:37], v[44:45]
	v_pk_add_f32 v[0:1], v[0:1], v[46:47]
	v_pk_add_f32 v[36:37], v[36:37], v[48:49]
	v_pk_add_f32 v[0:1], v[0:1], v[50:51]
	v_pk_add_f32 v[36:37], v[36:37], v[52:53]
	v_pk_add_f32 v[0:1], v[0:1], v[54:55]
	v_pk_add_f32 v[36:37], v[36:37], v[56:57]
	v_pk_add_f32 v[0:1], v[0:1], v[58:59]
	v_pk_add_f32 v[36:37], v[36:37], v[60:61]
	v_pk_add_f32 v[0:1], v[0:1], v[62:63]
	v_pk_add_f32 v[36:37], v[36:37], v[64:65]
	v_pk_add_f32 v[0:1], v[0:1], v[66:67]
	v_add_f32_e32 v2, v36, v37
	v_add_f32_e32 v0, v0, v2
	v_add_f32_e32 v0, v1, v0
	v_fmamk_f32 v0, v0, 0x3a000000, v197
	v_mul_f32_e32 v1, 0x4b800000, v0
	v_cmp_gt_f32_e32 vcc, s75, v0
	s_nop 1
	v_cndmask_b32_e32 v0, v0, v1, vcc
	v_rsq_f32_e32 v0, v0
	s_nop 0
	v_mul_f32_e32 v1, 0x45800000, v0
	v_cndmask_b32_e32 v0, v0, v1, vcc
	ds_write_b32 v150, v0
	v_pk_add_f32 v[68:69], v[68:69], v[72:73]
	v_pk_add_f32 v[0:1], v[70:71], v[74:75]
	v_pk_add_f32 v[68:69], v[68:69], v[76:77]
	v_pk_add_f32 v[0:1], v[0:1], v[78:79]
	v_pk_add_f32 v[68:69], v[68:69], v[80:81]
	v_pk_add_f32 v[0:1], v[0:1], v[82:83]
	v_pk_add_f32 v[68:69], v[68:69], v[84:85]
	v_pk_add_f32 v[0:1], v[0:1], v[86:87]
	v_pk_add_f32 v[68:69], v[68:69], v[88:89]
	v_pk_add_f32 v[0:1], v[0:1], v[90:91]
	v_pk_add_f32 v[68:69], v[68:69], v[92:93]
	v_pk_add_f32 v[0:1], v[0:1], v[94:95]
	v_pk_add_f32 v[68:69], v[68:69], v[96:97]
	v_pk_add_f32 v[0:1], v[0:1], v[98:99]
	v_add_f32_e32 v2, v68, v69
	v_add_f32_e32 v0, v0, v2
	v_add_f32_e32 v0, v1, v0
	v_fmamk_f32 v0, v0, 0x3a000000, v197
	v_mul_f32_e32 v1, 0x4b800000, v0
	v_cmp_gt_f32_e32 vcc, s75, v0
	s_nop 1
	v_cndmask_b32_e32 v0, v0, v1, vcc
	v_rsq_f32_e32 v0, v0
	s_nop 0
	v_mul_f32_e32 v1, 0x45800000, v0
	v_cndmask_b32_e32 v0, v0, v1, vcc
	ds_write_b32 v150, v0 offset:1024
	v_pk_add_f32 v[100:101], v[100:101], v[104:105]
	v_pk_add_f32 v[0:1], v[102:103], v[106:107]
	v_pk_add_f32 v[100:101], v[100:101], v[108:109]
	v_pk_add_f32 v[0:1], v[0:1], v[110:111]
	v_pk_add_f32 v[100:101], v[100:101], v[112:113]
	v_pk_add_f32 v[0:1], v[0:1], v[114:115]
	v_pk_add_f32 v[100:101], v[100:101], v[116:117]
	v_pk_add_f32 v[0:1], v[0:1], v[118:119]
	v_pk_add_f32 v[100:101], v[100:101], v[120:121]
	v_pk_add_f32 v[0:1], v[0:1], v[122:123]
	v_pk_add_f32 v[100:101], v[100:101], v[124:125]
	v_pk_add_f32 v[0:1], v[0:1], v[126:127]
	v_pk_add_f32 v[100:101], v[100:101], v[128:129]
	v_pk_add_f32 v[0:1], v[0:1], v[130:131]
	v_add_f32_e32 v2, v100, v101
	v_add_f32_e32 v0, v0, v2
	v_add_f32_e32 v0, v1, v0
	v_fmamk_f32 v0, v0, 0x3a000000, v197
	v_mul_f32_e32 v1, 0x4b800000, v0
	v_cmp_gt_f32_e32 vcc, s75, v0
	s_nop 1
	v_cndmask_b32_e32 v0, v0, v1, vcc
	v_rsq_f32_e32 v0, v0
	s_nop 0
	v_mul_f32_e32 v1, 0x45800000, v0
	v_cndmask_b32_e32 v0, v0, v1, vcc
	ds_write_b32 v150, v0 offset:2048
	v_pk_add_f32 v[152:153], v[152:153], v[156:157]
	v_pk_add_f32 v[0:1], v[154:155], v[158:159]
	v_pk_add_f32 v[152:153], v[152:153], v[160:161]
	v_pk_add_f32 v[0:1], v[0:1], v[162:163]
	v_pk_add_f32 v[152:153], v[152:153], v[164:165]
	v_pk_add_f32 v[0:1], v[0:1], v[166:167]
	v_pk_add_f32 v[152:153], v[152:153], v[168:169]
	v_pk_add_f32 v[0:1], v[0:1], v[170:171]
	v_pk_add_f32 v[152:153], v[152:153], v[172:173]
	v_pk_add_f32 v[0:1], v[0:1], v[174:175]
	v_pk_add_f32 v[152:153], v[152:153], v[176:177]
	v_pk_add_f32 v[0:1], v[0:1], v[178:179]
	v_pk_add_f32 v[152:153], v[152:153], v[180:181]
	v_pk_add_f32 v[0:1], v[0:1], v[182:183]
	v_add_f32_e32 v2, v152, v153
	v_add_f32_e32 v0, v0, v2
	v_add_f32_e32 v0, v1, v0
	v_fmamk_f32 v0, v0, 0x3a000000, v197
	v_mul_f32_e32 v1, 0x4b800000, v0
	v_cmp_gt_f32_e32 vcc, s75, v0
	s_nop 1
	v_cndmask_b32_e32 v0, v0, v1, vcc
	v_rsq_f32_e32 v0, v0
	s_nop 0
	v_mul_f32_e32 v1, 0x45800000, v0
	v_cndmask_b32_e32 v0, v0, v1, vcc
	ds_write_b32 v150, v0 offset:3072
; #define PG8_STAGE(bufoff, gbase, voff) do { _Pragma("unroll") for (int _i = 0; _i < 2; ++_i) \
;         __builtin_amdgcn_global_load_lds((const unsigned*)((const char*)(gbase) + (voff)[_i]), (LAS unsigned*)(lds + (bufoff) + ldsw + _i * 8192), 16, 0, 0); } while (0)
; #define PG8_WAIT_V(n) asm volatile("s_waitcnt vmcnt(" #n ")" ::: "memory")
; #define PG8_BAR __builtin_amdgcn_s_barrier()
; template <class Epi>
; __device__ __forceinline__ void gemm_phase(const Lt& lt, LAS unsigned char* lds, const Gemm g, const StaticOrder& S, const Epi& E) {
;     ...
;     for (int i = 0; i < 2; ++i) { int R, C; stage_rc(tid * 16 + i * 8192, R, C); const int Rb = (R & ~31) + perm32(R & 31);
;         voffA[i] = (unsigned)(R * K + C) * 2u; voffB[i] = (unsigned)(Rb * K + C) * 2u; }
;     const size_t kstep = (size_t)(BK * 2);
;     const size_t hstep = (size_t)HALF * K * 2;
;     const size_t tstep = 2 * hstep;
;     const unsigned ldsw = (unsigned)wid * 1024u;
;     const int aoff = lds_byte(wr * 64 + fr, fq * 8), boff = lds_byte(wc * 32 + fr, fq * 8);
;     ...
;     const char* cA = (const char*)g.A + (size_t)cur.pm * tstep; const char* cB = (const char*)g.Bt + (size_t)cur.pn * tstep;
;     PG8_STAGE(PG8_SB(0, 0), cB, voffB); PG8_STAGE(PG8_SB(0, 1), cB + hstep, voffB); PG8_STAGE(PG8_SA(0, 0), cA, voffA); PG8_STAGE(PG8_SA(0, 1), cA + hstep, voffA);
;     if (wr == 1) PG8_BAR;
;     PG8_WAIT_V(2); PG8_BAR;
.Lrs_done_b:
	s_or_b64 exec, exec, s[34:35]
	v_ashrrev_i32_e32 v0, 31, v245
	v_lshrrev_b32_e32 v0, 26, v0
	v_add_u32_e32 v0, v245, v0
	s_waitcnt vmcnt(0)
	v_ashrrev_i32_e32 v12, 6, v0
	v_bfe_i32 v0, v245, 27, 1
	v_lshlrev_b32_e32 v1, 4, v245
	v_lshrrev_b32_e32 v0, 22, v0
	v_add_u32_e32 v0, v1, v0
	v_and_b32_e32 v0, 0xfffffc00, v0
	v_sub_u32_e32 v0, v1, v0
	s_waitcnt lgkmcnt(0)
	v_lshrrev_b32_e32 v2, 4, v0
	v_readlane_b32 s0, v254, 1
	v_bitop3_b32 v0, v2, v0, 32 bitop3:0x6c
	s_add_u32 s53, s62, 0x1ae00000
	v_readlane_b32 s1, v254, 2
	v_ashrrev_i32_e32 v4, 31, v0
	s_addc_u32 s54, s63, 0
	s_mov_b32 s4, s0
	s_ashr_i32 s5, s0, 31
	v_writelane_b32 v254, s0, 1
	v_lshrrev_b32_e32 v4, 26, v4
	v_add_u32_e32 v4, v0, v4
	v_writelane_b32 v254, s1, 2
	s_lshl_b64 s[0:1], s[4:5], 25
	s_add_u32 s0, s62, s0
	v_lshlrev_b32_e32 v2, 3, v12
	v_ashrrev_i32_e32 v13, 6, v4
	v_and_b32_e32 v4, 0xc0, v4
	s_addc_u32 s1, s63, s1
	v_and_b32_e32 v2, -16, v2
	v_sub_u32_e32 v0, v0, v4
	s_add_u32 s55, s0, 0x6c00000
	v_add_u32_e32 v2, v13, v2
	v_ashrrev_i16_sdwa v0, v241, sext(v0) dst_sel:DWORD dst_unused:UNUSED_PAD src0_sel:DWORD src1_sel:BYTE_0
	s_addc_u32 s56, s1, 0
	v_lshlrev_b32_e32 v5, 5, v12
	v_bfe_i32 v14, v0, 0, 16
	v_lshlrev_b32_e32 v0, 1, v2
	v_lshrrev_b32_e32 v4, 2, v2
	v_and_b32_e32 v6, 3, v13
	s_mov_b32 s1, 0xfffe0
	v_and_b32_e32 v5, 32, v5
	v_and_b32_e32 v0, 24, v0
	v_and_b32_e32 v4, 4, v4
	v_and_or_b32 v6, v2, s1, v6
	v_or3_b32 v4, v6, v4, v0
	v_add_lshl_u32 v5, v5, v14, 1
	v_add_u32_e32 v1, 0x2000, v1
	v_lshl_add_u32 v0, v2, 12, v5
	v_lshl_add_u32 v2, v4, 12, v5
	v_ashrrev_i32_e32 v4, 31, v1
	v_lshrrev_b32_e32 v4, 22, v4
	v_add_u32_e32 v4, v1, v4
	v_ashrrev_i32_e32 v15, 10, v4
	v_mul_i32_i24_e32 v4, 0x400, v15
	v_sub_u32_e32 v1, v1, v4
	v_lshrrev_b32_e32 v4, 4, v1
	v_bitop3_b32 v1, v4, v1, 32 bitop3:0x6c
	v_ashrrev_i32_e32 v5, 31, v1
	v_lshrrev_b32_e32 v5, 26, v5
	v_lshlrev_b32_e32 v4, 3, v15
	v_add_u32_e32 v5, v1, v5
	v_and_b32_e32 v4, -16, v4
	v_ashrrev_i32_e32 v16, 6, v5
	v_add_u32_e32 v4, v16, v4
	v_and_b32_e32 v7, 3, v16
	v_and_b32_e32 v5, 0xc0, v5
	v_and_or_b32 v7, v4, s1, v7
	s_ashr_i32 s1, s10, 6
	s_ashr_i32 s29, s28, 31
	s_ashr_i32 s31, s30, 31
	s_ashr_i32 s0, s10, 8
	v_sub_u32_e32 v1, v1, v5
	s_lshl_b32 s57, s1, 10
	s_lshl_b64 s[34:35], s[28:29], 20
	s_lshl_b64 s[4:5], s[30:31], 20
	v_ashrrev_i16_sdwa v1, v241, sext(v1) dst_sel:DWORD dst_unused:UNUSED_PAD src0_sel:DWORD src1_sel:BYTE_0
	s_add_u32 s4, s55, s4
	v_lshlrev_b32_e32 v6, 5, v15
	v_bfe_i32 v17, v1, 0, 16
	v_lshlrev_b32_e32 v1, 1, v4
	v_lshrrev_b32_e32 v5, 2, v4
	s_addc_u32 s5, s56, s5
	s_add_i32 s29, s57, 0
	v_and_b32_e32 v6, 32, v6
	v_and_b32_e32 v1, 24, v1
	v_and_b32_e32 v5, 4, v5
	s_add_i32 m0, s29, 0x10000
	v_or3_b32 v1, v7, v5, v1
	v_add_lshl_u32 v5, v6, v17, 1
	global_load_lds_dwordx4 v2, s[4:5]
	s_add_i32 m0, s29, 0x12000
	v_lshl_add_u32 v134, v1, 12, v5
	s_add_u32 s36, s4, 0x80000
	global_load_lds_dwordx4 v134, s[4:5]
	s_addc_u32 s37, s5, 0
	s_add_i32 m0, s29, 0x14000
	v_lshl_add_u32 v132, v4, 12, v5
	global_load_lds_dwordx4 v2, s[36:37]
	s_add_i32 m0, s29, 0x16000
	s_add_u32 s42, s53, s34
	s_addc_u32 s43, s54, s35
	s_add_i32 s31, s29, 0x2000
	global_load_lds_dwordx4 v134, s[36:37]
	s_mov_b32 m0, s29
	s_add_u32 s34, s42, 0x80000
	global_load_lds_dwordx4 v0, s[42:43]
	s_mov_b32 m0, s31
	s_addc_u32 s35, s43, 0
	s_add_i32 s58, s29, 0x4000
	global_load_lds_dwordx4 v132, s[42:43]
	s_mov_b32 m0, s58
	s_add_i32 s59, s29, 0x6000
	global_load_lds_dwordx4 v0, s[34:35]
	s_mov_b32 m0, s59
	v_mov_b32_e32 v135, v3
	global_load_lds_dwordx4 v132, s[34:35]
	v_mov_b32_e32 v1, v3
	v_mov_b32_e32 v133, v3
	v_lshl_add_u64 v[10:11], s[4:5], 0, v[2:3]
	v_lshl_add_u64 v[8:9], s[4:5], 0, v[134:135]
	v_lshl_add_u64 v[6:7], s[42:43], 0, v[0:1]
	s_cmp_eq_u32 s0, 1
	v_lshl_add_u64 v[4:5], s[42:43], 0, v[132:133]
	s_cbranch_scc0 .LBB0_69
	s_barrier

; __device__ __forceinline__ float row_rstd(const float* ssq, int row, float inv_n) {
;     const f32x4* p = (const f32x4*)(ssq + (size_t)row * 32);
;     f32x4 s = p[0];
; #pragma unroll
;     for (int i = 1; i < 8; ++i) s += p[i];
;     return rsqrtf((s[0] + s[1] + s[2] + s[3]) * inv_n + NORM_EPS);
; }
;     __device__ bool next(int i, Unit& u) const {
;         const long L = (long)i * G + c; if (L >= nwg) return false;
;         int wgid = (int)L; { const int q = nwg / NXCD, r = nwg % NXCD, xcd = wgid % NXCD, off = wgid / NXCD; wgid = (xcd < r ? xcd * (q + 1) : r * (q + 1) + (xcd - r) * q) + off; }
;         const int nig = WGM * nN, gid = wgid / nig, fm = gid * WGM, gsz = (nM - fm) < WGM ? (nM - fm) : WGM;
;         u.pm = fm + ((wgid % nig) % gsz); u.pn = (wgid % nig) / gsz; return true;
;     }
.LBB0_395:
	v_readlane_b32 s4, v254, 1
	v_readlane_b32 s5, v254, 2
	s_mov_b32 s6, s4
	s_mul_i32 s5, s6, 0x1300000
	v_readlane_b32 s42, v253, 63
	s_mul_hi_i32 s4, s4, 0x1300000
	v_readlane_b32 s43, v254, 0
	s_add_u32 s6, s42, s5
	s_addc_u32 s7, s43, s4
	s_andn2_b64 vcc, exec, s[0:1]
	s_cbranch_vccnz .LBB0_434
	v_readlane_b32 s0, v253, 16
	s_add_u32 s8, s42, 0x1ce00000
	s_addc_u32 s9, s43, 0
	v_lshl_add_u32 v146, v245, 2, s0
	s_movk_i32 s0, 0x100
	v_cmp_gt_i32_e64 s[0:1], s0, v245
	s_and_saveexec_b64 s[4:5], s[0:1]
	s_cbranch_execz .LBB0_398
	s_ashr_i32 s29, s86, 31
	s_lshr_b32 s29, s29, 29
	s_add_i32 s29, s86, s29
	s_and_b32 s31, s29, -8
	s_sub_i32 s31, s86, s31
	s_cmp_lt_i32 s31, 0
	s_movk_i32 s34, 0x4d
	s_cselect_b32 s34, s34, 0x4c
	s_mul_i32 s31, s31, s34
	s_ashr_i32 s29, s29, 3
	s_add_i32 s31, s31, s29
	s_mul_hi_i32 s29, s31, 0x6bca1af3
	s_lshr_b32 s34, s29, 31
	s_ashr_i32 s29, s29, 6
	s_add_i32 s29, s29, s34
	s_mul_i32 s34, s29, 0x98
	s_sub_i32 s31, s31, s34
	s_bfe_u32 s34, s31, 0x3001c
	s_add_i32 s34, s31, s34
	s_and_b32 s34, s34, 0xfff8
	s_sub_i32 s31, s31, s34
	s_sext_i32_i16 s31, s31
	s_lshl_b32 s29, s29, 11
	s_lshl_b32 s31, s31, 8
	s_add_i32 s31, s31, s29
	v_add_u32_e32 v0, s31, v245
	v_ashrrev_i32_e32 v1, 31, v0
	v_lshlrev_b64 v[0:1], 7, v[0:1]
	v_lshl_add_u64 v[0:1], s[8:9], 0, v[0:1]
	s_waitcnt lgkmcnt(0)
	global_load_dwordx4 v[36:39], v[0:1], off
	global_load_dwordx4 v[40:43], v[0:1], off offset:16
	global_load_dwordx4 v[44:47], v[0:1], off offset:32
	global_load_dwordx4 v[48:51], v[0:1], off offset:48
	global_load_dwordx4 v[52:55], v[0:1], off offset:64
	global_load_dwordx4 v[56:59], v[0:1], off offset:80
	global_load_dwordx4 v[60:63], v[0:1], off offset:96
	global_load_dwordx4 v[64:67], v[0:1], off offset:112
.LBB0_398:
	s_or_b64 exec, exec, s[4:5]
	s_ashr_i32 s52, s86, 31
	s_add_u32 s4, s86, s89
	s_addc_u32 s5, s52, s87
	v_cmp_gt_i64_e32 vcc, s[4:5], v[200:201]
	s_cbranch_vccnz .LBB0_419
	s_and_saveexec_b64 s[34:35], s[0:1]
	s_cbranch_execz .LBB0_401
	s_ashr_i32 s29, s4, 31
	s_lshr_b32 s29, s29, 29
	s_add_i32 s29, s4, s29
	s_ashr_i32 s31, s29, 3
	s_and_b32 s29, s29, -8
	s_sub_i32 s29, s4, s29
	s_cmp_lt_i32 s29, 0
	s_movk_i32 s36, 0x4d
	s_cselect_b32 s36, s36, 0x4c
	s_mul_i32 s29, s29, s36
	s_add_i32 s29, s29, s31
	s_mul_hi_i32 s31, s29, 0x6bca1af3
	s_lshr_b32 s36, s31, 31
	s_ashr_i32 s31, s31, 6
	s_add_i32 s31, s31, s36
	s_lshl_b32 s36, s31, 3
	s_sub_i32 s37, 32, s36
	s_min_i32 s37, s37, 8
	s_abs_i32 s37, s37
	v_cvt_f32_u32_e32 v0, s37
	s_sub_i32 s38, 0, s37
	s_mulk_i32 s31, 0x98
	s_sub_i32 s29, s29, s31
	v_rcp_iflag_f32_e32 v0, v0
	s_ashr_i32 s31, s29, 31
	s_abs_i32 s29, s29
	v_mul_f32_e32 v0, 0x4f7ffffe, v0
	v_cvt_u32_f32_e32 v0, v0
	s_nop 0
	v_readfirstlane_b32 s39, v0
	s_mul_i32 s38, s38, s39
	s_mul_hi_u32 s38, s39, s38
	s_add_i32 s39, s39, s38
	s_mul_hi_u32 s38, s29, s39
	s_mul_i32 s38, s38, s37
	s_sub_i32 s29, s29, s38
	s_sub_i32 s38, s29, s37
	s_cmp_ge_u32 s29, s37
	s_cselect_b32 s29, s38, s29
	s_sub_i32 s38, s29, s37
	s_cmp_ge_u32 s29, s37
	s_cselect_b32 s29, s38, s29
	s_xor_b32 s29, s29, s31
	s_sub_i32 s29, s29, s31
	s_add_i32 s29, s29, s36
	v_lshl_add_u32 v0, s29, 8, v245
	v_ashrrev_i32_e32 v1, 31, v0
	v_lshlrev_b64 v[0:1], 7, v[0:1]
	v_lshl_add_u64 v[0:1], s[8:9], 0, v[0:1]
	s_waitcnt lgkmcnt(0)
	global_load_dwordx4 v[68:71], v[0:1], off
	global_load_dwordx4 v[72:75], v[0:1], off offset:16
	global_load_dwordx4 v[76:79], v[0:1], off offset:32
	global_load_dwordx4 v[80:83], v[0:1], off offset:48
	global_load_dwordx4 v[84:87], v[0:1], off offset:64
	global_load_dwordx4 v[88:91], v[0:1], off offset:80
	global_load_dwordx4 v[92:95], v[0:1], off offset:96
	global_load_dwordx4 v[96:99], v[0:1], off offset:112
; __device__ __forceinline__ float row_rstd(const float* ssq, int row, float inv_n) {
;     const f32x4* p = (const f32x4*)(ssq + (size_t)row * 32);
;     f32x4 s = p[0];
; #pragma unroll
;     for (int i = 1; i < 8; ++i) s += p[i];
;     return rsqrtf((s[0] + s[1] + s[2] + s[3]) * inv_n + NORM_EPS);
; }
;     __device__ bool next(int i, Unit& u) const {
;         const long L = (long)i * G + c; if (L >= nwg) return false;
;         int wgid = (int)L; { const int q = nwg / NXCD, r = nwg % NXCD, xcd = wgid % NXCD, off = wgid / NXCD; wgid = (xcd < r ? xcd * (q + 1) : r * (q + 1) + (xcd - r) * q) + off; }
;         const int nig = WGM * nN, gid = wgid / nig, fm = gid * WGM, gsz = (nM - fm) < WGM ? (nM - fm) : WGM;
;         u.pm = fm + ((wgid % nig) % gsz); u.pn = (wgid % nig) / gsz; return true;
;     }
.LBB0_401:
	s_or_b64 exec, exec, s[34:35]
	s_add_u32 s4, s4, s89
	s_addc_u32 s5, s5, s87
	v_cmp_gt_i64_e32 vcc, s[4:5], v[200:201]
	s_cbranch_vccnz .LBB0_419
	s_and_saveexec_b64 s[34:35], s[0:1]
	s_cbranch_execz .LBB0_404
	s_ashr_i32 s29, s4, 31
	s_lshr_b32 s29, s29, 29
	s_add_i32 s29, s4, s29
	s_ashr_i32 s31, s29, 3
	s_and_b32 s29, s29, -8
	s_sub_i32 s29, s4, s29
	s_cmp_lt_i32 s29, 0
	s_movk_i32 s36, 0x4d
	s_cselect_b32 s36, s36, 0x4c
	s_mul_i32 s29, s29, s36
	s_add_i32 s29, s29, s31
	s_mul_hi_i32 s31, s29, 0x6bca1af3
	s_lshr_b32 s36, s31, 31
	s_ashr_i32 s31, s31, 6
	s_add_i32 s31, s31, s36
	s_lshl_b32 s36, s31, 3
	s_sub_i32 s37, 32, s36
	s_min_i32 s37, s37, 8
	s_abs_i32 s37, s37
	v_cvt_f32_u32_e32 v0, s37
	s_sub_i32 s38, 0, s37
	s_mulk_i32 s31, 0x98
	s_sub_i32 s29, s29, s31
	v_rcp_iflag_f32_e32 v0, v0
	s_ashr_i32 s31, s29, 31
	s_abs_i32 s29, s29
	v_mul_f32_e32 v0, 0x4f7ffffe, v0
	v_cvt_u32_f32_e32 v0, v0
	s_nop 0
	v_readfirstlane_b32 s39, v0
	s_mul_i32 s38, s38, s39
	s_mul_hi_u32 s38, s39, s38
	s_add_i32 s39, s39, s38
	s_mul_hi_u32 s38, s29, s39
	s_mul_i32 s38, s38, s37
	s_sub_i32 s29, s29, s38
	s_sub_i32 s38, s29, s37
	s_cmp_ge_u32 s29, s37
	s_cselect_b32 s29, s38, s29
	s_sub_i32 s38, s29, s37
	s_cmp_ge_u32 s29, s37
	s_cselect_b32 s29, s38, s29
	s_xor_b32 s29, s29, s31
	s_sub_i32 s29, s29, s31
	s_add_i32 s29, s29, s36
	v_lshl_add_u32 v0, s29, 8, v245
	v_ashrrev_i32_e32 v1, 31, v0
	v_lshlrev_b64 v[0:1], 7, v[0:1]
	v_lshl_add_u64 v[0:1], s[8:9], 0, v[0:1]
	s_waitcnt lgkmcnt(0)
	global_load_dwordx4 v[100:103], v[0:1], off
	global_load_dwordx4 v[104:107], v[0:1], off offset:16
	global_load_dwordx4 v[108:111], v[0:1], off offset:32
	global_load_dwordx4 v[112:115], v[0:1], off offset:48
	global_load_dwordx4 v[116:119], v[0:1], off offset:64
	global_load_dwordx4 v[120:123], v[0:1], off offset:80
	global_load_dwordx4 v[124:127], v[0:1], off offset:96
	global_load_dwordx4 v[128:131], v[0:1], off offset:112
.LBB0_404:
	s_or_b64 exec, exec, s[34:35]
	s_add_u32 s4, s4, s89
	s_addc_u32 s5, s5, s87
	v_cmp_gt_i64_e32 vcc, s[4:5], v[200:201]
	s_cbranch_vccnz .LBB0_419
	s_and_saveexec_b64 s[34:35], s[0:1]
	s_cbranch_execz .LBB0_407
	s_ashr_i32 s29, s4, 31
	s_lshr_b32 s29, s29, 29
	s_add_i32 s29, s4, s29
	s_ashr_i32 s31, s29, 3
	s_and_b32 s29, s29, -8
	s_sub_i32 s29, s4, s29
	s_cmp_lt_i32 s29, 0
	s_movk_i32 s36, 0x4d
	s_cselect_b32 s36, s36, 0x4c
	s_mul_i32 s29, s29, s36
	s_add_i32 s29, s29, s31
	s_mul_hi_i32 s31, s29, 0x6bca1af3
	s_lshr_b32 s36, s31, 31
	s_ashr_i32 s31, s31, 6
	s_add_i32 s31, s31, s36
	s_lshl_b32 s36, s31, 3
	s_sub_i32 s37, 32, s36
	s_min_i32 s37, s37, 8
	s_abs_i32 s37, s37
	v_cvt_f32_u32_e32 v0, s37
	s_sub_i32 s38, 0, s37
	s_mulk_i32 s31, 0x98
	s_sub_i32 s29, s29, s31
	v_rcp_iflag_f32_e32 v0, v0
	s_ashr_i32 s31, s29, 31
	s_abs_i32 s29, s29
	v_mul_f32_e32 v0, 0x4f7ffffe, v0
	v_cvt_u32_f32_e32 v0, v0
	s_nop 0
	v_readfirstlane_b32 s39, v0
	s_mul_i32 s38, s38, s39
	s_mul_hi_u32 s38, s39, s38
	s_add_i32 s39, s39, s38
	s_mul_hi_u32 s38, s29, s39
	s_mul_i32 s38, s38, s37
	s_sub_i32 s29, s29, s38
	s_sub_i32 s38, s29, s37
	s_cmp_ge_u32 s29, s37
	s_cselect_b32 s29, s38, s29
	s_sub_i32 s38, s29, s37
	s_cmp_ge_u32 s29, s37
	s_cselect_b32 s29, s38, s29
	s_xor_b32 s29, s29, s31
	s_sub_i32 s29, s29, s31
	s_add_i32 s29, s29, s36
	v_lshl_add_u32 v0, s29, 8, v245
	v_ashrrev_i32_e32 v1, 31, v0
	v_lshlrev_b64 v[0:1], 7, v[0:1]
	v_lshl_add_u64 v[0:1], s[8:9], 0, v[0:1]
	s_waitcnt lgkmcnt(0)
	global_load_dwordx4 v[152:155], v[0:1], off
	global_load_dwordx4 v[156:159], v[0:1], off offset:16
	global_load_dwordx4 v[160:163], v[0:1], off offset:32
	global_load_dwordx4 v[164:167], v[0:1], off offset:48
	global_load_dwordx4 v[168:171], v[0:1], off offset:64
	global_load_dwordx4 v[172:175], v[0:1], off offset:80
	global_load_dwordx4 v[176:179], v[0:1], off offset:96
	global_load_dwordx4 v[180:183], v[0:1], off offset:112

; #define PG8_STAGE(bufoff, gbase, voff) do { _Pragma("unroll") for (int _i = 0; _i < 2; ++_i) \
;         __builtin_amdgcn_global_load_lds((const unsigned*)((const char*)(gbase) + (voff)[_i]), (LAS unsigned*)(lds + (bufoff) + ldsw + _i * 8192), 16, 0, 0); } while (0)
; #define PG8_WAIT_V(n) asm volatile("s_waitcnt vmcnt(" #n ")" ::: "memory")
; #define PG8_BAR __builtin_amdgcn_s_barrier()
; __device__ __forceinline__ float row_rstd(const float* ssq, int row, float inv_n) {
;     const f32x4* p = (const f32x4*)(ssq + (size_t)row * 32);
;     f32x4 s = p[0];
; #pragma unroll
;     for (int i = 1; i < 8; ++i) s += p[i];
;     return rsqrtf((s[0] + s[1] + s[2] + s[3]) * inv_n + NORM_EPS);
; }
; template <class Epi>
; __device__ __forceinline__ void gemm_phase(const Lt& lt, LAS unsigned char* lds, const Gemm g, const StaticOrder& S, const Epi& E) {
;     ...
;     for (int i = 0; i < 2; ++i) { int R, C; stage_rc(tid * 16 + i * 8192, R, C); const int Rb = (R & ~31) + perm32(R & 31);
;         voffA[i] = (unsigned)(R * K + C) * 2u; voffB[i] = (unsigned)(Rb * K + C) * 2u; }
;     const size_t kstep = (size_t)(BK * 2);
;     const size_t hstep = (size_t)HALF * K * 2;
;     const size_t tstep = 2 * hstep;
;     const unsigned ldsw = (unsigned)wid * 1024u;
;     const int aoff = lds_byte(wr * 64 + fr, fq * 8), boff = lds_byte(wc * 32 + fr, fq * 8);
;     ...
;     Unit cur, nxt; int ui = 0;
;     if (!S.next(0, cur)) return;
;     { Unit uu; for (int i = 0; i < 8 && S.next(i, uu); ++i) E.prepare(uu, lds, i, tid); }
;     f32x4 acc[2][2][4][2];
; #pragma unroll
;     for (int a = 0; a < 2; ++a)
; #pragma unroll
;         for (int b = 0; b < 2; ++b)
; #pragma unroll
;             for (int m = 0; m < 4; ++m)
; #pragma unroll
;                 for (int n = 0; n < 2; ++n) acc[a][b][m][n] = (f32x4){0.f, 0.f, 0.f, 0.f};
;     bf16x8 At[4][2], B0[2][2], B1[2][2];
;     const char* cA = (const char*)g.A + (size_t)cur.pm * tstep; const char* cB = (const char*)g.Bt + (size_t)cur.pn * tstep;
;     PG8_STAGE(PG8_SB(0, 0), cB, voffB); PG8_STAGE(PG8_SB(0, 1), cB + hstep, voffB); PG8_STAGE(PG8_SA(0, 0), cA, voffA); PG8_STAGE(PG8_SA(0, 1), cA + hstep, voffA);
;     if (wr == 1) PG8_BAR;
;     PG8_WAIT_V(2); PG8_BAR;
.LBB0_419:
	s_movk_i32 s34, 0x100
	v_cmp_gt_i32_e32 vcc, s34, v245
	s_and_saveexec_b64 s[34:35], vcc
	s_cbranch_execz .Lrs_done_a
	s_waitcnt vmcnt(0)
	v_pk_add_f32 v[36:37], v[36:37], v[40:41]
	v_pk_add_f32 v[0:1], v[38:39], v[42:43]
	v_pk_add_f32 v[36:37], v[36:37], v[44:45]
	v_pk_add_f32 v[0:1], v[0:1], v[46:47]
	v_pk_add_f32 v[36:37], v[36:37], v[48:49]
	v_pk_add_f32 v[0:1], v[0:1], v[50:51]
	v_pk_add_f32 v[36:37], v[36:37], v[52:53]
	v_pk_add_f32 v[0:1], v[0:1], v[54:55]
	v_pk_add_f32 v[36:37], v[36:37], v[56:57]
	v_pk_add_f32 v[0:1], v[0:1], v[58:59]
	v_pk_add_f32 v[36:37], v[36:37], v[60:61]
	v_pk_add_f32 v[0:1], v[0:1], v[62:63]
	v_pk_add_f32 v[36:37], v[36:37], v[64:65]
	v_pk_add_f32 v[0:1], v[0:1], v[66:67]
	v_add_f32_e32 v2, v36, v37
	v_add_f32_e32 v0, v0, v2
	v_add_f32_e32 v0, v1, v0
	v_fmamk_f32 v0, v0, 0x3a000000, v197
	v_mul_f32_e32 v1, 0x4b800000, v0
	v_cmp_gt_f32_e32 vcc, s75, v0
	s_nop 1
	v_cndmask_b32_e32 v0, v0, v1, vcc
	v_rsq_f32_e32 v0, v0
	s_nop 0
	v_mul_f32_e32 v1, 0x45800000, v0
	v_cndmask_b32_e32 v0, v0, v1, vcc
	ds_write_b32 v146, v0
	v_pk_add_f32 v[68:69], v[68:69], v[72:73]
	v_pk_add_f32 v[0:1], v[70:71], v[74:75]
	v_pk_add_f32 v[68:69], v[68:69], v[76:77]
	v_pk_add_f32 v[0:1], v[0:1], v[78:79]
	v_pk_add_f32 v[68:69], v[68:69], v[80:81]
	v_pk_add_f32 v[0:1], v[0:1], v[82:83]
	v_pk_add_f32 v[68:69], v[68:69], v[84:85]
	v_pk_add_f32 v[0:1], v[0:1], v[86:87]
	v_pk_add_f32 v[68:69], v[68:69], v[88:89]
	v_pk_add_f32 v[0:1], v[0:1], v[90:91]
	v_pk_add_f32 v[68:69], v[68:69], v[92:93]
	v_pk_add_f32 v[0:1], v[0:1], v[94:95]
	v_pk_add_f32 v[68:69], v[68:69], v[96:97]
	v_pk_add_f32 v[0:1], v[0:1], v[98:99]
	v_add_f32_e32 v2, v68, v69
	v_add_f32_e32 v0, v0, v2
	v_add_f32_e32 v0, v1, v0
	v_fmamk_f32 v0, v0, 0x3a000000, v197
	v_mul_f32_e32 v1, 0x4b800000, v0
	v_cmp_gt_f32_e32 vcc, s75, v0
	s_nop 1
	v_cndmask_b32_e32 v0, v0, v1, vcc
	v_rsq_f32_e32 v0, v0
	s_nop 0
	v_mul_f32_e32 v1, 0x45800000, v0
	v_cndmask_b32_e32 v0, v0, v1, vcc
	ds_write_b32 v146, v0 offset:1024
	s_cmpk_ge_u32 s86, 0x60
	s_cbranch_scc1 .Lrs_done_a
	v_pk_add_f32 v[100:101], v[100:101], v[104:105]
	v_pk_add_f32 v[0:1], v[102:103], v[106:107]
	v_pk_add_f32 v[100:101], v[100:101], v[108:109]
	v_pk_add_f32 v[0:1], v[0:1], v[110:111]
	v_pk_add_f32 v[100:101], v[100:101], v[112:113]
	v_pk_add_f32 v[0:1], v[0:1], v[114:115]
	v_pk_add_f32 v[100:101], v[100:101], v[116:117]
	v_pk_add_f32 v[0:1], v[0:1], v[118:119]
	v_pk_add_f32 v[100:101], v[100:101], v[120:121]
	v_pk_add_f32 v[0:1], v[0:1], v[122:123]
	v_pk_add_f32 v[100:101], v[100:101], v[124:125]
	v_pk_add_f32 v[0:1], v[0:1], v[126:127]
	v_pk_add_f32 v[100:101], v[100:101], v[128:129]
	v_pk_add_f32 v[0:1], v[0:1], v[130:131]
	v_add_f32_e32 v2, v100, v101
	v_add_f32_e32 v0, v0, v2
	v_add_f32_e32 v0, v1, v0
	v_fmamk_f32 v0, v0, 0x3a000000, v197
	v_mul_f32_e32 v1, 0x4b800000, v0
	v_cmp_gt_f32_e32 vcc, s75, v0
	s_nop 1
	v_cndmask_b32_e32 v0, v0, v1, vcc
	v_rsq_f32_e32 v0, v0
	s_nop 0
	v_mul_f32_e32 v1, 0x45800000, v0
	v_cndmask_b32_e32 v0, v0, v1, vcc
	ds_write_b32 v146, v0 offset:2048
.Lrs_done_a:
	s_or_b64 exec, exec, s[34:35]
	v_ashrrev_i32_e32 v0, 31, v245
	v_lshrrev_b32_e32 v0, 26, v0
	v_add_u32_e32 v0, v245, v0
	s_waitcnt vmcnt(0)
	v_ashrrev_i32_e32 v12, 6, v0
	v_bfe_i32 v0, v245, 27, 1
	v_lshlrev_b32_e32 v1, 4, v245
	v_lshrrev_b32_e32 v0, 22, v0
	v_add_u32_e32 v0, v1, v0
	v_and_b32_e32 v0, 0xfffffc00, v0
	v_sub_u32_e32 v0, v1, v0
	s_waitcnt lgkmcnt(0)
	v_lshrrev_b32_e32 v2, 4, v0
	v_bitop3_b32 v0, v2, v0, 32 bitop3:0x6c
	s_waitcnt lgkmcnt(0)
	v_ashrrev_i32_e32 v4, 31, v0
	v_lshrrev_b32_e32 v4, 26, v4
	v_add_u32_e32 v4, v0, v4
	v_lshlrev_b32_e32 v2, 3, v12
	v_ashrrev_i32_e32 v13, 6, v4
	v_and_b32_e32 v4, 0xc0, v4
	v_and_b32_e32 v2, -16, v2
	v_sub_u32_e32 v0, v0, v4
	v_add_u32_e32 v2, v13, v2
	v_ashrrev_i16_sdwa v0, v241, sext(v0) dst_sel:DWORD dst_unused:UNUSED_PAD src0_sel:DWORD src1_sel:BYTE_0
	v_lshlrev_b32_e32 v5, 5, v12
	v_bfe_i32 v14, v0, 0, 16
	v_lshlrev_b32_e32 v0, 1, v2
	v_lshrrev_b32_e32 v4, 2, v2
	v_and_b32_e32 v6, 3, v13
	s_mov_b32 s5, 0xfffe0
	v_and_b32_e32 v5, 32, v5
	v_and_b32_e32 v0, 24, v0
	v_and_b32_e32 v4, 4, v4
	v_and_or_b32 v6, v2, s5, v6
	v_or3_b32 v4, v6, v4, v0
	v_add_lshl_u32 v5, v5, v14, 1
	v_add_u32_e32 v1, 0x2000, v1
	v_lshl_add_u32 v0, v2, 12, v5
	v_lshl_add_u32 v2, v4, 12, v5
	v_ashrrev_i32_e32 v4, 31, v1
	v_lshrrev_b32_e32 v4, 22, v4
	v_add_u32_e32 v4, v1, v4
	v_ashrrev_i32_e32 v15, 10, v4
	v_mul_i32_i24_e32 v4, 0x400, v15
	v_sub_u32_e32 v1, v1, v4
	v_lshrrev_b32_e32 v4, 4, v1
	v_bitop3_b32 v1, v4, v1, 32 bitop3:0x6c
	v_ashrrev_i32_e32 v5, 31, v1
	v_lshrrev_b32_e32 v5, 26, v5
	v_lshlrev_b32_e32 v4, 3, v15
	v_add_u32_e32 v5, v1, v5
	v_and_b32_e32 v4, -16, v4
	v_ashrrev_i32_e32 v16, 6, v5
	s_add_u32 s53, s42, 0x1ae00000
	v_add_u32_e32 v4, v16, v4
	v_and_b32_e32 v7, 3, v16
	s_addc_u32 s54, s43, 0
	v_and_b32_e32 v5, 0xc0, v5
	v_and_or_b32 v7, v4, s5, v7
	s_ashr_i32 s5, s10, 6
	s_ashr_i32 s29, s28, 31
	s_ashr_i32 s31, s30, 31
	s_ashr_i32 s4, s10, 8
	v_sub_u32_e32 v1, v1, v5
	s_lshl_b32 s55, s5, 10
	s_lshl_b64 s[34:35], s[28:29], 20
	s_lshl_b64 s[36:37], s[30:31], 20
	v_ashrrev_i16_sdwa v1, v241, sext(v1) dst_sel:DWORD dst_unused:UNUSED_PAD src0_sel:DWORD src1_sel:BYTE_0
	s_add_u32 s46, s6, s36
	v_lshlrev_b32_e32 v6, 5, v15
	v_bfe_i32 v17, v1, 0, 16
	v_lshlrev_b32_e32 v1, 1, v4
	v_lshrrev_b32_e32 v5, 2, v4
	s_addc_u32 s47, s7, s37
	s_add_i32 s31, s55, 0
	v_and_b32_e32 v6, 32, v6
	v_and_b32_e32 v1, 24, v1
	v_and_b32_e32 v5, 4, v5
	s_add_i32 m0, s31, 0x10000
	v_or3_b32 v1, v7, v5, v1
	v_add_lshl_u32 v5, v6, v17, 1
	global_load_lds_dwordx4 v2, s[46:47]
	s_add_i32 m0, s31, 0x12000
	v_lshl_add_u32 v134, v1, 12, v5
	s_add_u32 s36, s46, 0x80000
	global_load_lds_dwordx4 v134, s[46:47]
	s_addc_u32 s37, s47, 0
	s_add_i32 m0, s31, 0x14000
	v_lshl_add_u32 v132, v4, 12, v5
	global_load_lds_dwordx4 v2, s[36:37]
	s_add_i32 m0, s31, 0x16000
	s_add_u32 s40, s53, s34
	s_addc_u32 s41, s54, s35
	s_add_i32 s56, s31, 0x2000
	global_load_lds_dwordx4 v134, s[36:37]
	s_mov_b32 m0, s31
	s_add_u32 s34, s40, 0x80000
	global_load_lds_dwordx4 v0, s[40:41]
	s_mov_b32 m0, s56
	s_addc_u32 s35, s41, 0
	s_add_i32 s57, s31, 0x4000
	global_load_lds_dwordx4 v132, s[40:41]
	s_mov_b32 m0, s57
	s_add_i32 s58, s31, 0x6000
	global_load_lds_dwordx4 v0, s[34:35]
	s_mov_b32 m0, s58
	v_mov_b32_e32 v135, v3
	global_load_lds_dwordx4 v132, s[34:35]
	v_mov_b32_e32 v1, v3
	v_mov_b32_e32 v133, v3
	v_lshl_add_u64 v[10:11], s[46:47], 0, v[2:3]
	v_lshl_add_u64 v[8:9], s[46:47], 0, v[134:135]
	v_lshl_add_u64 v[6:7], s[40:41], 0, v[0:1]
	s_cmp_eq_u32 s4, 1
	v_lshl_add_u64 v[4:5], s[40:41], 0, v[132:133]
	s_cbranch_scc0 .LBB0_421
	s_barrier
